# DSA pair loop: next pair's mask words consumed from their load registers (8 v_mov_b64 per pair removed), mask loads issued after the fragment build
# speedup vs baseline: 1.0026x; 1.0026x over previous
.LBB0_718:
	s_waitcnt vmcnt(0)
	s_add_i32 s50, s50, 1
	s_cmp_ge_u32 s50, s72
	s_waitcnt lgkmcnt(0)
	s_barrier
	s_cbranch_scc1 .LBB0_720
	s_add_i32 s4, s51, 2
	s_add_i32 s5, s51, 3
	s_cmp_lt_u32 s4, s71
	s_cselect_b32 s4, s5, s71
	s_and_b32 s5, s16, 0x8000
	s_add_i32 s6, s54, s5
	s_lshl_b32 s4, s4, 6
	v_mad_u64_u32 v[84:85], s[4:5], s4, v199, v[170:171]
	s_mov_b32 m0, s6
	v_lshl_add_u64 v[86:87], v[84:85], 0, v[2:3]
	global_load_lds_dwordx4 v[174:175], off
	s_add_i32 m0, s6, 0x2000
	v_mov_b32_e32 v179, v3
	global_load_lds_dwordx4 v[176:177], off
	v_lshl_add_u64 v[86:87], v[86:87], 0, s[38:39]
	s_add_i32 m0, s6, 0x4000
	v_lshl_add_u64 v[84:85], v[84:85], 0, v[178:179]
	global_load_lds_dwordx4 v[86:87], off
	v_lshl_add_u64 v[84:85], v[84:85], 0, s[44:45]
	s_add_i32 m0, s6, 0x6000
	s_nop 0
	global_load_lds_dwordx4 v[84:85], off
.LBB0_720:
	v_mov_b32_e32 v90, 0
	v_mov_b32_e32 v84, v254
	v_mov_b32_e32 v85, v255
.LBB0_722:
	v_mov_b32_e32 v92, v90
	v_mov_b32_e32 v93, v90
	v_mov_b32_e32 v88, v90
	v_mov_b32_e32 v89, v90
	s_and_saveexec_b64 s[4:5], s[10:11]
	s_cbranch_execz .LBB0_724
	v_bfe_u32 v68, v152, v215, 1
	v_bfe_u32 v72, v148, v215, 1
	v_lshl_or_b32 v68, v72, 16, v68
	v_mad_i32_i24 v93, v68, s98, v252
	v_bfe_u32 v68, v161, v215, 1
	v_bfe_u32 v72, v157, v215, 1
	v_lshl_or_b32 v68, v72, 16, v68
	v_mad_i32_i24 v88, v68, s98, v252
	v_bfe_u32 v76, v160, v215, 1
	v_bfe_u32 v80, v156, v215, 1
	v_lshl_or_b32 v76, v80, 16, v76
	v_mad_i32_i24 v92, v76, s98, v252
	v_bfe_u32 v68, v153, v215, 1
	v_bfe_u32 v69, v149, v215, 1
	v_lshl_or_b32 v68, v69, 16, v68
	v_mad_i32_i24 v89, v68, s98, v252
.LBB0_724:
	s_or_b64 exec, exec, s[4:5]
	v_mov_b32_e32 v98, 0
	v_mov_b32_e32 v116, 0
	v_mov_b32_e32 v117, 0
	v_mov_b32_e32 v96, 0
	v_mov_b32_e32 v97, 0
	s_and_saveexec_b64 s[4:5], s[10:11]
	s_cbranch_execz .LBB0_726
	v_bfe_u32 v68, v162, v215, 1
	v_bfe_u32 v69, v158, v215, 1
	v_lshl_or_b32 v68, v69, 16, v68
	v_mad_i32_i24 v116, v68, s98, v252
	v_bfe_u32 v68, v154, v215, 1
	v_bfe_u32 v69, v150, v215, 1
	v_lshl_or_b32 v68, v69, 16, v68
	v_mad_i32_i24 v117, v68, s98, v252
	v_bfe_u32 v68, v163, v215, 1
	v_bfe_u32 v69, v159, v215, 1
	v_lshl_or_b32 v68, v69, 16, v68
	v_mad_i32_i24 v96, v68, s98, v252
	v_bfe_u32 v68, v155, v215, 1
	v_bfe_u32 v69, v151, v215, 1
	v_lshl_or_b32 v68, v69, 16, v68
	v_mad_i32_i24 v97, v68, s98, v252
.LBB0_726:
	s_or_b64 exec, exec, s[4:5]
	s_cmp_ge_u32 s50, s72
	s_cbranch_scc1 .Ldsa_nomask
	global_load_dwordx4 v[160:163], v3, s[52:53] offset:-768
	global_load_dwordx4 v[156:159], v3, s[52:53] offset:-512
	global_load_dwordx4 v[152:155], v3, s[52:53] offset:-256
	global_load_dwordx4 v[148:151], v3, s[52:53]
.Ldsa_nomask:
	v_mov_b32_e32 v94, v90
	v_mov_b32_e32 v95, v90
	v_mov_b32_e32 v91, v90
	s_add_i32 s4, s16, 0xffff8000
	v_mov_b32_e32 v86, v90
	v_mov_b32_e32 v87, v90
	s_and_b32 s4, s4, 0x8000
	s_add_i32 s73, s4, 0
	v_mfma_f32_32x32x16_bf16 v[100:115], v[92:95], v[84:87], 0
	v_add_u32_e32 v99, s73, v201
	v_add_u32_e32 v179, v99, v165
	v_add_u32_e32 v187, v99, v216
	v_add_u32_e32 v192, v99, v217
	v_add_u32_e32 v193, v99, v218
	v_mov_b32_e32 v118, v98
	v_mov_b32_e32 v119, v98
	v_mfma_f32_32x32x16_bf16 v[68:83], v[88:91], v[84:87], 0
	ds_read_b128 v[88:91], v179
	ds_read_b128 v[92:95], v179 offset:4096
	v_mov_b32_e32 v99, v98
	s_cmp_lt_u32 s51, s71
	s_cselect_b64 s[4:5], -1, 0
	s_waitcnt lgkmcnt(0)
	v_mfma_f32_32x32x16_bf16 v[100:115], v[88:91], v[132:135], v[100:115]
	v_mfma_f32_32x32x16_bf16 v[68:83], v[92:95], v[132:135], v[68:83]
	ds_read_b128 v[88:91], v187
	ds_read_b128 v[92:95], v187 offset:4096
	s_waitcnt lgkmcnt(0)
	v_mfma_f32_32x32x16_bf16 v[100:115], v[88:91], v[136:139], v[100:115]
	v_mfma_f32_32x32x16_bf16 v[68:83], v[92:95], v[136:139], v[68:83]
	ds_read_b128 v[88:91], v192
	ds_read_b128 v[92:95], v192 offset:4096
	s_waitcnt lgkmcnt(0)
	v_mfma_f32_32x32x16_bf16 v[100:115], v[88:91], v[140:143], v[100:115]
	v_mfma_f32_32x32x16_bf16 v[68:83], v[92:95], v[140:143], v[68:83]
	ds_read_b128 v[88:91], v193
	ds_read_b128 v[92:95], v193 offset:4096
	ds_read_b128 v[182:185], v179 offset:16384
	ds_read_b128 v[188:191], v179 offset:20480
	v_mfma_f32_32x32x16_bf16 v[116:131], v[116:119], v[84:87], 0
	s_waitcnt lgkmcnt(0)
	v_mfma_f32_32x32x16_bf16 v[100:115], v[88:91], v[144:147], v[100:115]
	v_mfma_f32_32x32x16_bf16 v[68:83], v[92:95], v[144:147], v[68:83]
	v_mfma_f32_32x32x16_bf16 v[84:99], v[96:99], v[84:87], 0
	s_nop 10
	v_max_f32_e32 v179, v68, v68
	v_mfma_f32_32x32x16_bf16 v[116:131], v[182:185], v[132:135], v[116:131]
	v_mfma_f32_32x32x16_bf16 v[84:99], v[188:191], v[132:135], v[84:99]
	ds_read_b128 v[182:185], v187 offset:16384
	ds_read_b128 v[188:191], v187 offset:20480
	v_max_f32_e32 v187, v100, v100
	v_max_f32_e32 v179, v187, v179
	v_max3_f32 v179, v179, v101, v69
	v_max3_f32 v179, v179, v102, v70
	s_waitcnt lgkmcnt(0)
; #define LAS __attribute__((address_space(3)))
; #define MFMA32(a, b, c) __builtin_amdgcn_mfma_f32_32x32x16_bf16((a), (b), (c), 0, 0, 0)
; DI float fexp2(float x) { return __builtin_amdgcn_exp2f(x); }
; DI float half_max(float v) { return fmaxf(v, __shfl_xor(v, 32)); }
; DI void flash_qk_bias(const LAS unsigned char* kb, const bf16x8 (&qf)[4], f32x16& p0, f32x16& p1, int r32, int h, const bf16x8& m0, const bf16x8& m1, const bf16x8& ef) {
;     p0 = MFMA32(m0, ef, f16zero()); p1 = MFMA32(m1, ef, f16zero());
;     const int sw = (r32 >> 1) & 7;
; #pragma unroll
;     for (int s = 0; s < 4; ++s) {
;         const int off = r32 * 128 + (((2 * s + h) ^ sw) << 4);
;         const bf16x8 a0 = *(const LAS bf16x8*)(kb + off), a1 = *(const LAS bf16x8*)(kb + off + 4096);
;         p0 = MFMA32(a0, qf[s], p0); p1 = MFMA32(a1, qf[s], p1);
;     }
; DI void flash_pv2(FState& sa, FState& sb, f32x16& a0, f32x16& a1, bool rona, f32x16& b0, f32x16& b1, bool ronb, const LAS unsigned char* va, const LAS unsigned char* vbb, int lane) {
;     float mxa = fmaxf(a0[0], a1[0]), mxb = fmaxf(b0[0], b1[0]);
; #pragma unroll
;     for (int r = 1; r < 16; ++r) { asm("v_max3_f32 %0, %1, %2, %3" : "=v"(mxa) : "v"(mxa), "v"(a0[r]), "v"(a1[r])); asm("v_max3_f32 %0, %1, %2, %3" : "=v"(mxb) : "v"(mxb), "v"(b0[r]), "v"(b1[r])); }
;     mxa = half_max(mxa); mxb = half_max(mxb);
;     mxa = rona ? mxa : NINF; mxb = ronb ? mxb : NINF;
;     const bool upa = mxa > sa.m + THR_RAW, upb = mxb > sb.m + THR_RAW;
;     if (__any(upa || upb)) {
;         const float mna = upa ? mxa : sa.m, mnb = upb ? mxb : sb.m;
;         const float ala = upa ? fexp2((sa.m - mna) * SM_C) : 1.0f, alb = upb ? fexp2((sb.m - mnb) * SM_C) : 1.0f;
;         sa.m = mna; sa.l *= ala; sb.m = mnb; sb.l *= alb;
; #pragma unroll
;         for (int r = 0; r < 16; ++r) { sa.o0[r] *= ala; sa.o1[r] *= ala; sb.o0[r] *= alb; sb.o1[r] *= alb; }
;     }
	v_mfma_f32_32x32x16_bf16 v[116:131], v[182:185], v[136:139], v[116:131]
	v_max3_f32 v179, v179, v103, v71
	v_max3_f32 v179, v179, v104, v72
	v_max3_f32 v179, v179, v105, v73
	v_max3_f32 v179, v179, v106, v74
	v_mfma_f32_32x32x16_bf16 v[84:99], v[188:191], v[136:139], v[84:99]
	ds_read_b128 v[182:185], v192 offset:16384
	ds_read_b128 v[188:191], v192 offset:20480
	v_max3_f32 v179, v179, v107, v75
	v_max3_f32 v179, v179, v108, v76
	v_max3_f32 v179, v179, v109, v77
	s_waitcnt lgkmcnt(0)
	v_mfma_f32_32x32x16_bf16 v[116:131], v[182:185], v[140:143], v[116:131]
	ds_read_b128 v[182:185], v193 offset:20480
	v_max3_f32 v179, v179, v110, v78
	v_max3_f32 v179, v179, v111, v79
	v_max3_f32 v179, v179, v112, v80
	v_mfma_f32_32x32x16_bf16 v[84:99], v[188:191], v[140:143], v[84:99]
	v_max3_f32 v179, v179, v113, v81
	v_max3_f32 v179, v179, v114, v82
	s_waitcnt lgkmcnt(0)
	v_mfma_f32_32x32x16_bf16 v[84:99], v[182:185], v[144:147], v[84:99]
	ds_read_b128 v[182:185], v193 offset:16384
	s_waitcnt lgkmcnt(0)
	v_mfma_f32_32x32x16_bf16 v[116:131], v[182:185], v[144:147], v[116:131]
	s_nop 8
	v_max_f32_e32 v187, v84, v84
	v_and_b32_e32 v184, 64, v198
	v_max3_f32 v183, v179, v115, v83
	v_xor_b32_e32 v179, 32, v198
	v_add_u32_e32 v184, 64, v184
	v_cmp_lt_i32_e32 vcc, v179, v184
	v_max_f32_e32 v182, v116, v116
	v_max_f32_e32 v182, v182, v187
	v_max3_f32 v182, v182, v117, v85
	v_cndmask_b32_e32 v179, v198, v179, vcc
	v_max3_f32 v182, v182, v118, v86
	v_lshlrev_b32_e32 v179, 2, v179
	v_max3_f32 v182, v182, v119, v87
	ds_bpermute_b32 v184, v179, v183
	v_max3_f32 v182, v182, v120, v88
	v_max3_f32 v182, v182, v121, v89
	v_max3_f32 v182, v182, v122, v90
	v_max3_f32 v182, v182, v123, v91
	v_max3_f32 v182, v182, v124, v92
	v_max3_f32 v182, v182, v125, v93
	v_max3_f32 v182, v182, v126, v94
	v_max3_f32 v182, v182, v127, v95
	v_max3_f32 v182, v182, v128, v96
	v_max3_f32 v182, v182, v129, v97
	v_max3_f32 v182, v182, v130, v98
	v_max3_f32 v185, v182, v131, v99
	ds_bpermute_b32 v187, v179, v185
	v_max_f32_e32 v182, v183, v183
	s_waitcnt lgkmcnt(0)
	v_max_f32_e32 v183, v184, v184
	v_max_f32_e32 v182, v182, v183
	v_max_f32_e32 v183, v185, v185
	v_max_f32_e32 v184, v187, v187
	v_max_f32_e32 v183, v183, v184
	v_cndmask_b32_e64 v183, v186, v183, s[4:5]
	v_pk_add_f32 v[184:185], v[180:181], s[46:47] op_sel_hi:[1,0]
	s_nop 0
	v_cmp_gt_f32_e64 s[6:7], v182, v184
	v_cmp_gt_f32_e64 s[8:9], v183, v185
	s_or_b64 vcc, s[6:7], s[8:9]
	s_cbranch_vccz .LBB0_728
	v_cndmask_b32_e64 v183, v181, v183, s[8:9]
	v_cndmask_b32_e64 v182, v180, v182, s[6:7]
	v_pk_add_f32 v[180:181], v[180:181], v[182:183] neg_lo:[0,1] neg_hi:[0,1]
	s_nop 0
	v_mul_f32_e32 v180, 0x3e38aa3b, v180
	v_mul_f32_e32 v181, 0x3e38aa3b, v181
	v_exp_f32_e32 v181, v181
	v_exp_f32_e32 v180, v180
	v_cndmask_b32_e64 v181, 1.0, v181, s[8:9]
	v_cndmask_b32_e64 v180, 1.0, v180, s[6:7]
	v_pk_mul_f32 v[172:173], v[172:173], v[180:181]
	v_pk_mul_f32 v[66:67], v[66:67], v[180:181] op_sel_hi:[1,0]
	v_pk_mul_f32 v[64:65], v[64:65], v[180:181] op_sel_hi:[1,0]
	v_pk_mul_f32 v[62:63], v[62:63], v[180:181] op_sel_hi:[1,0]
	v_pk_mul_f32 v[60:61], v[60:61], v[180:181] op_sel_hi:[1,0]
	v_pk_mul_f32 v[58:59], v[58:59], v[180:181] op_sel_hi:[1,0]
	v_pk_mul_f32 v[56:57], v[56:57], v[180:181] op_sel_hi:[1,0]
	v_pk_mul_f32 v[54:55], v[54:55], v[180:181] op_sel_hi:[1,0]
	v_pk_mul_f32 v[52:53], v[52:53], v[180:181] op_sel_hi:[1,0]
	v_pk_mul_f32 v[18:19], v[18:19], v[180:181] op_sel_hi:[1,0]
	v_pk_mul_f32 v[16:17], v[16:17], v[180:181] op_sel_hi:[1,0]
	v_pk_mul_f32 v[14:15], v[14:15], v[180:181] op_sel_hi:[1,0]
	v_pk_mul_f32 v[12:13], v[12:13], v[180:181] op_sel_hi:[1,0]
	v_pk_mul_f32 v[10:11], v[10:11], v[180:181] op_sel_hi:[1,0]
	v_pk_mul_f32 v[8:9], v[8:9], v[180:181] op_sel_hi:[1,0]
	v_pk_mul_f32 v[6:7], v[6:7], v[180:181] op_sel_hi:[1,0]
	v_pk_mul_f32 v[4:5], v[4:5], v[180:181] op_sel_hi:[1,0]
	v_mov_b32_e32 v180, v181
	v_pk_mul_f32 v[50:51], v[50:51], v[180:181] op_sel_hi:[1,0]
	v_pk_mul_f32 v[48:49], v[48:49], v[180:181] op_sel_hi:[1,0]
	v_pk_mul_f32 v[46:47], v[46:47], v[180:181] op_sel_hi:[1,0]
	v_pk_mul_f32 v[44:45], v[44:45], v[180:181] op_sel_hi:[1,0]
	v_pk_mul_f32 v[42:43], v[42:43], v[180:181] op_sel_hi:[1,0]
	v_pk_mul_f32 v[40:41], v[40:41], v[180:181] op_sel_hi:[1,0]
	v_pk_mul_f32 v[38:39], v[38:39], v[180:181] op_sel_hi:[1,0]
	v_pk_mul_f32 v[36:37], v[36:37], v[180:181] op_sel_hi:[1,0]
	v_pk_mul_f32 v[34:35], v[34:35], v[180:181] op_sel_hi:[1,0]
	v_pk_mul_f32 v[32:33], v[32:33], v[180:181] op_sel_hi:[1,0]
	v_pk_mul_f32 v[30:31], v[30:31], v[180:181] op_sel_hi:[1,0]
	v_pk_mul_f32 v[28:29], v[28:29], v[180:181] op_sel_hi:[1,0]
	v_pk_mul_f32 v[26:27], v[26:27], v[180:181] op_sel_hi:[1,0]
	v_pk_mul_f32 v[24:25], v[24:25], v[180:181] op_sel_hi:[1,0]
	v_pk_mul_f32 v[22:23], v[22:23], v[180:181] op_sel_hi:[1,0]
	v_pk_mul_f32 v[20:21], v[20:21], v[180:181] op_sel_hi:[1,0]
	v_mov_b64_e32 v[180:181], v[182:183]

; #define LAS __attribute__((address_space(3)))
; #define MFMA32(a, b, c) __builtin_amdgcn_mfma_f32_32x32x16_bf16((a), (b), (c), 0, 0, 0)
; DI float fexp2(float x) { return __builtin_amdgcn_exp2f(x); }
; DI void flash_pv2(FState& sa, FState& sb, f32x16& a0, f32x16& a1, bool rona, f32x16& b0, f32x16& b1, bool ronb, const LAS unsigned char* va, const LAS unsigned char* vbb, int lane) {
;     ...
;     const float cla = rona ? SM_C : 0.0f, bla = rona ? ((sa.m == NINF) ? 0.0f : -sa.m * SM_C) : NINF;
;     const float clb = ronb ? SM_C : 0.0f, blb = ronb ? ((sb.m == NINF) ? 0.0f : -sb.m * SM_C) : NINF;
;     float suma = 0.f, sumb = 0.f;
; #pragma unroll
;     for (int r = 0; r < 16; ++r) {
;         a0[r] = fexp2(__builtin_fmaf(a0[r], cla, bla)); b0[r] = fexp2(__builtin_fmaf(b0[r], clb, blb));
;         a1[r] = fexp2(__builtin_fmaf(a1[r], cla, bla)); b1[r] = fexp2(__builtin_fmaf(b1[r], clb, blb));
;         suma += a0[r] + a1[r]; sumb += b0[r] + b1[r];
;     }
;     sa.l += suma; sb.l += sumb;
;     const int h = lane >> 5;
;     const int vx = (((lane & 15) >> 3) & 1) * 64;
;     const int voff = (4 * h + ((lane & 15) >> 2)) * 128 + ((lane >> 4) & 1) * 32 + (lane & 3) * 8;
; #pragma unroll
;     for (int sub = 0; sub < 2; ++sub)
; #pragma unroll
;         for (int s2 = 0; s2 < 2; ++s2) {
;             const bf16x8 pfa = pack8h(sub ? a1 : a0, s2), pfb = pack8h(sub ? b1 : b0, s2);
;             const LAS unsigned char* qa = va + voff + (32 * sub + 16 * s2) * 128; const LAS unsigned char* qb = vbb + voff + (32 * sub + 16 * s2) * 128;
;             { const s16x4 lo = vtr(qa + vx), hi = vtr(qa + 1024 + vx); const bf16x8 vf = {lo[0], lo[1], lo[2], lo[3], hi[0], hi[1], hi[2], hi[3]}; sa.o0 = MFMA32(vf, pfa, sa.o0); }
;             { const s16x4 lo = vtr(qb + vx), hi = vtr(qb + 1024 + vx); const bf16x8 vf = {lo[0], lo[1], lo[2], lo[3], hi[0], hi[1], hi[2], hi[3]}; sb.o0 = MFMA32(vf, pfb, sb.o0); }
;             { const s16x4 lo = vtr(qa + (64 - vx)), hi = vtr(qa + 1024 + (64 - vx)); const bf16x8 vf = {lo[0], lo[1], lo[2], lo[3], hi[0], hi[1], hi[2], hi[3]}; sa.o1 = MFMA32(vf, pfa, sa.o1); }
;             { const s16x4 lo = vtr(qb + (64 - vx)), hi = vtr(qb + 1024 + (64 - vx)); const bf16x8 vf = {lo[0], lo[1], lo[2], lo[3], hi[0], hi[1], hi[2], hi[3]}; sb.o1 = MFMA32(vf, pfb, sb.o1); }
;         }
.LBB0_733:
	v_mul_f32_e32 v182, 0xbe38aa3b, v180
	v_cmp_neq_f32_e32 vcc, s62, v180
	s_add_i32 s51, s51, 2
	s_add_i32 s16, s16, 0x8000
	v_cndmask_b32_e32 v221, 0, v182, vcc
	v_fmamk_f32 v68, v68, 0x3e38aa3b, v221
	v_fmamk_f32 v100, v100, 0x3e38aa3b, v221
	v_exp_f32_e32 v184, v68
	v_fma_f32 v68, s4, v84, v187
	v_exp_f32_e32 v182, v100
	v_fma_f32 v100, s4, v116, v187
	v_exp_f32_e32 v183, v68
	v_fmamk_f32 v68, v101, 0x3e38aa3b, v221
	v_exp_f32_e32 v185, v100
	v_exp_f32_e32 v100, v68
	v_fma_f32 v68, s4, v117, v187
	v_exp_f32_e32 v189, v68
	v_fmamk_f32 v68, v69, 0x3e38aa3b, v221
	v_fma_f32 v69, s4, v118, v187
	v_fmamk_f32 v74, v74, 0x3e38aa3b, v221
	v_exp_f32_e32 v117, v69
	v_fmamk_f32 v69, v70, 0x3e38aa3b, v221
	v_exp_f32_e32 v196, v74
	v_fma_f32 v74, s4, v90, v187
	v_exp_f32_e32 v188, v68
	v_fma_f32 v68, s4, v85, v187
	v_exp_f32_e32 v116, v69
	v_fma_f32 v69, s4, v86, v187
	v_fma_f32 v86, s4, v121, v187
	v_exp_f32_e32 v121, v74
	v_fmamk_f32 v74, v107, 0x3e38aa3b, v221
	v_exp_f32_e32 v101, v68
	v_fmamk_f32 v68, v102, 0x3e38aa3b, v221
	v_fmamk_f32 v72, v72, 0x3e38aa3b, v221
	v_fmamk_f32 v102, v106, 0x3e38aa3b, v221
	v_exp_f32_e32 v90, v74
	v_fma_f32 v74, s4, v123, v187
	v_fmamk_f32 v77, v77, 0x3e38aa3b, v221
	v_fmamk_f32 v70, v103, 0x3e38aa3b, v221
	v_fma_f32 v85, s4, v120, v187
	v_exp_f32_e32 v190, v72
	v_fma_f32 v72, s4, v88, v187
	v_exp_f32_e32 v120, v102
	v_fma_f32 v102, s4, v122, v187
	v_exp_f32_e32 v103, v74
	v_fmamk_f32 v74, v75, 0x3e38aa3b, v221
	v_fma_f32 v75, s4, v124, v187
	v_exp_f32_e32 v106, v77
	v_fma_f32 v77, s4, v93, v187
	v_fma_f32 v93, s4, v126, v187
	v_fmamk_f32 v71, v71, 0x3e38aa3b, v221
	v_exp_f32_e32 v191, v85
	v_exp_f32_e32 v85, v72
	v_fmamk_f32 v72, v105, 0x3e38aa3b, v221
	v_exp_f32_e32 v197, v102
	v_exp_f32_e32 v102, v74
	v_fma_f32 v74, s4, v91, v187
	v_exp_f32_e32 v105, v75
	v_fmamk_f32 v75, v76, 0x3e38aa3b, v221
	v_fmamk_f32 v76, v109, 0x3e38aa3b, v221
	v_exp_f32_e32 v109, v93
	v_fmamk_f32 v78, v78, 0x3e38aa3b, v221
	v_fma_f32 v93, s4, v127, v187
	v_exp_f32_e32 v68, v68
	v_exp_f32_e32 v69, v69
	v_fma_f32 v84, s4, v119, v187
	v_exp_f32_e32 v118, v71
	v_fma_f32 v71, s4, v87, v187
	v_exp_f32_e32 v91, v74
	v_fmamk_f32 v74, v108, 0x3e38aa3b, v221
	v_exp_f32_e32 v108, v78
	v_fmamk_f32 v78, v111, 0x3e38aa3b, v221
	v_exp_f32_e32 v111, v93
	v_fmamk_f32 v93, v112, 0x3e38aa3b, v221
	v_exp_f32_e32 v70, v70
	v_exp_f32_e32 v119, v84
	v_exp_f32_e32 v71, v71
	v_fmamk_f32 v84, v104, 0x3e38aa3b, v221
	v_fmamk_f32 v73, v73, 0x3e38aa3b, v221
	v_exp_f32_e32 v112, v93
	v_add_u32_e32 v93, s73, v219
	v_exp_f32_e32 v84, v84
	v_exp_f32_e32 v193, v86
	v_exp_f32_e32 v192, v73
	v_fma_f32 v73, s4, v89, v187
	v_pk_add_f32 v[86:87], v[182:183], v[184:185]
	v_cvt_pk_bf16_f32 v122, v182, v100
	v_add_u32_e32 v182, v93, v202
	v_exp_f32_e32 v72, v72
	v_exp_f32_e32 v73, v73
	v_pk_add_f32 v[86:87], v[86:87], 0 op_sel_hi:[1,0]
	v_pk_add_f32 v[88:89], v[100:101], v[188:189]
	s_waitcnt vmcnt(0)
	ds_read_b64_tr_b16 v[222:223], v182 offset:8192
	ds_read_b64_tr_b16 v[224:225], v182 offset:9216
	v_pk_add_f32 v[86:87], v[88:89], v[86:87]
	v_pk_add_f32 v[88:89], v[68:69], v[116:117]
	v_cvt_pk_bf16_f32 v123, v68, v70
	v_pk_add_f32 v[86:87], v[88:89], v[86:87]
	v_pk_add_f32 v[88:89], v[70:71], v[118:119]
	ds_read_b64_tr_b16 v[230:231], v182 offset:24576
	ds_read_b64_tr_b16 v[232:233], v182 offset:25600
	ds_read_b64_tr_b16 v[234:235], v182 offset:10240
	ds_read_b64_tr_b16 v[236:237], v182 offset:11264
	v_fma_f32 v68, s4, v128, v187
	v_pk_add_f32 v[86:87], v[88:89], v[86:87]
	v_pk_add_f32 v[88:89], v[84:85], v[190:191]
	v_exp_f32_e32 v247, v68
	v_fmamk_f32 v68, v113, 0x3e38aa3b, v221
	v_pk_add_f32 v[86:87], v[88:89], v[86:87]
	v_pk_add_f32 v[88:89], v[72:73], v[192:193]
	v_exp_f32_e32 v104, v75
	v_fma_f32 v75, s4, v92, v187
	v_fma_f32 v92, s4, v125, v187
	v_cvt_pk_bf16_f32 v124, v84, v72
	v_cvt_pk_bf16_f32 v125, v120, v90
	v_cvt_pk_bf16_f32 v226, v185, v189
	v_cvt_pk_bf16_f32 v227, v117, v119
	v_cvt_pk_bf16_f32 v228, v191, v193
	v_cvt_pk_bf16_f32 v229, v197, v103
	v_add_u32_e32 v72, v93, v220
	v_exp_f32_e32 v248, v68
	v_fma_f32 v68, s4, v129, v187
	s_waitcnt lgkmcnt(4)
	v_mfma_f32_32x32x16_bf16 v[52:67], v[222:225], v[122:125], v[52:67]
	ds_read_b64_tr_b16 v[222:223], v72 offset:8256
	ds_read_b64_tr_b16 v[224:225], v72 offset:9280
	ds_read_b64_tr_b16 v[238:239], v182 offset:26624
	ds_read_b64_tr_b16 v[240:241], v182 offset:27648
	v_exp_f32_e32 v251, v68
	v_fmamk_f32 v68, v114, 0x3e38aa3b, v221
	v_exp_f32_e32 v84, v68
	v_fma_f32 v68, s4, v130, v187
	v_exp_f32_e32 v107, v92
	v_fmamk_f32 v92, v110, 0x3e38aa3b, v221
	s_waitcnt lgkmcnt(6)
	v_mfma_f32_32x32x16_bf16 v[36:51], v[230:233], v[226:229], v[36:51]
	ds_read_b64_tr_b16 v[230:231], v72 offset:24640
	ds_read_b64_tr_b16 v[232:233], v72 offset:25664
	ds_read_b64_tr_b16 v[242:243], v72 offset:10304
	ds_read_b64_tr_b16 v[244:245], v72 offset:11328
	v_fmamk_f32 v70, v115, 0x3e38aa3b, v221
	v_exp_f32_e32 v189, v68
	v_fma_f32 v68, s4, v131, v187
	v_exp_f32_e32 v74, v74
	v_exp_f32_e32 v76, v76
	v_exp_f32_e32 v92, v92
	v_exp_f32_e32 v78, v78
	s_waitcnt lgkmcnt(6)
; #define LAS __attribute__((address_space(3)))
; #define MFMA32(a, b, c) __builtin_amdgcn_mfma_f32_32x32x16_bf16((a), (b), (c), 0, 0, 0)
; DI float fexp2(float x) { return __builtin_amdgcn_exp2f(x); }
; DI s16x4 vtr(const LAS unsigned char* p) { return __builtin_bit_cast(s16x4, __builtin_amdgcn_ds_read_tr16_b64_v4i16((LAS v4i16_t*)p)); }
; DI void flash_pv2(FState& sa, FState& sb, f32x16& a0, f32x16& a1, bool rona, f32x16& b0, f32x16& b1, bool ronb, const LAS unsigned char* va, const LAS unsigned char* vbb, int lane) {
;     ...
;     for (int r = 0; r < 16; ++r) {
;         a0[r] = fexp2(__builtin_fmaf(a0[r], cla, bla)); b0[r] = fexp2(__builtin_fmaf(b0[r], clb, blb));
;         a1[r] = fexp2(__builtin_fmaf(a1[r], cla, bla)); b1[r] = fexp2(__builtin_fmaf(b1[r], clb, blb));
;         suma += a0[r] + a1[r]; sumb += b0[r] + b1[r];
;     }
;     sa.l += suma; sb.l += sumb;
;     const int h = lane >> 5;
;     const int vx = (((lane & 15) >> 3) & 1) * 64;
;     const int voff = (4 * h + ((lane & 15) >> 2)) * 128 + ((lane >> 4) & 1) * 32 + (lane & 3) * 8;
; #pragma unroll
;     for (int sub = 0; sub < 2; ++sub)
; #pragma unroll
;         for (int s2 = 0; s2 < 2; ++s2) {
;             const bf16x8 pfa = pack8h(sub ? a1 : a0, s2), pfb = pack8h(sub ? b1 : b0, s2);
;             const LAS unsigned char* qa = va + voff + (32 * sub + 16 * s2) * 128; const LAS unsigned char* qb = vbb + voff + (32 * sub + 16 * s2) * 128;
;             { const s16x4 lo = vtr(qa + vx), hi = vtr(qa + 1024 + vx); const bf16x8 vf = {lo[0], lo[1], lo[2], lo[3], hi[0], hi[1], hi[2], hi[3]}; sa.o0 = MFMA32(vf, pfa, sa.o0); }
;             { const s16x4 lo = vtr(qb + vx), hi = vtr(qb + 1024 + vx); const bf16x8 vf = {lo[0], lo[1], lo[2], lo[3], hi[0], hi[1], hi[2], hi[3]}; sb.o0 = MFMA32(vf, pfb, sb.o0); }
;             { const s16x4 lo = vtr(qa + (64 - vx)), hi = vtr(qa + 1024 + (64 - vx)); const bf16x8 vf = {lo[0], lo[1], lo[2], lo[3], hi[0], hi[1], hi[2], hi[3]}; sa.o1 = MFMA32(vf, pfa, sa.o1); }
;             { const s16x4 lo = vtr(qb + (64 - vx)), hi = vtr(qb + 1024 + (64 - vx)); const bf16x8 vf = {lo[0], lo[1], lo[2], lo[3], hi[0], hi[1], hi[2], hi[3]}; sb.o1 = MFMA32(vf, pfb, sb.o1); }
;         }
; DI void dsa_task(LAS unsigned char* lds, const bf16_t* Z, const unsigned* dmask, bf16_t* YB, int b, int qi, int tid, int wave, int lane) {
;     ...
;     for (int p0_ = 0; p0_ < npair; ++p0_) DSA_PAIR(p0_);
	v_mfma_f32_32x32x16_bf16 v[4:19], v[222:225], v[122:125], v[4:19]
	v_exp_f32_e32 v100, v70
	v_exp_f32_e32 v131, v68
	ds_read_b64_tr_b16 v[122:123], v72 offset:26688
	ds_read_b64_tr_b16 v[124:125], v72 offset:27712
	v_cvt_pk_bf16_f32 v126, v74, v76
	v_cvt_pk_bf16_f32 v127, v92, v78
	v_cvt_pk_bf16_f32 v128, v112, v248
	v_cvt_pk_bf16_f32 v129, v84, v100
	s_waitcnt lgkmcnt(4)
	v_mfma_f32_32x32x16_bf16 v[20:35], v[230:233], v[226:229], v[20:35]
	v_cvt_pk_bf16_f32 v222, v105, v107
	v_cvt_pk_bf16_f32 v223, v109, v111
	v_cvt_pk_bf16_f32 v224, v247, v251
	v_cvt_pk_bf16_f32 v225, v189, v131
	v_fma_f32 v68, s4, v94, v187
	v_exp_f32_e32 v93, v68
	v_fmamk_f32 v68, v79, 0x3e38aa3b, v221
	v_mfma_f32_32x32x16_bf16 v[52:67], v[234:237], v[126:129], v[52:67]
	v_exp_f32_e32 v110, v68
	v_fma_f32 v68, s4, v95, v187
	v_exp_f32_e32 v79, v68
	v_fmamk_f32 v68, v80, 0x3e38aa3b, v221
	v_exp_f32_e32 v246, v68
	v_fma_f32 v68, s4, v96, v187
	v_exp_f32_e32 v113, v68
	v_mfma_f32_32x32x16_bf16 v[36:51], v[238:241], v[222:225], v[36:51]
	v_fmamk_f32 v68, v81, 0x3e38aa3b, v221
	v_cvt_pk_bf16_f32 v95, v116, v118
	v_exp_f32_e32 v250, v68
	v_fma_f32 v68, s4, v97, v187
	v_exp_f32_e32 v249, v68
	v_cvt_pk_bf16_f32 v94, v184, v188
	v_cvt_pk_bf16_f32 v96, v190, v192
	s_waitcnt lgkmcnt(2)
	v_mfma_f32_32x32x16_bf16 v[4:19], v[242:245], v[126:129], v[4:19]
	v_cvt_pk_bf16_f32 v97, v196, v102
	v_cvt_pk_bf16_f32 v68, v183, v101
	v_cvt_pk_bf16_f32 v69, v69, v71
	v_cvt_pk_bf16_f32 v70, v85, v73
	v_cvt_pk_bf16_f32 v71, v121, v91
	v_pk_add_f32 v[86:87], v[88:89], v[86:87]
	v_pk_add_f32 v[88:89], v[120:121], v[196:197]
	s_waitcnt lgkmcnt(0)
	v_mfma_f32_32x32x16_bf16 v[20:35], v[122:125], v[222:225], v[20:35]
	ds_read_b64_tr_b16 v[122:123], v182 offset:12288
	ds_read_b64_tr_b16 v[124:125], v182 offset:13312
	ds_read_b64_tr_b16 v[114:115], v182 offset:28672
	ds_read_b64_tr_b16 v[116:117], v182 offset:29696
	ds_read_b64_tr_b16 v[126:127], v182 offset:14336
	ds_read_b64_tr_b16 v[128:129], v182 offset:15360
	v_fmamk_f32 v73, v82, 0x3e38aa3b, v221
	v_exp_f32_e32 v75, v75
	v_exp_f32_e32 v188, v73
	v_fma_f32 v73, s4, v98, v187
	v_fmac_f32_e32 v221, 0x3e38aa3b, v83
	s_waitcnt lgkmcnt(4)
	v_mfma_f32_32x32x16_bf16 v[52:67], v[122:125], v[94:97], v[52:67]
	ds_read_b64_tr_b16 v[118:119], v72 offset:12352
	ds_read_b64_tr_b16 v[120:121], v72 offset:13376
	ds_read_b64_tr_b16 v[122:123], v182 offset:30720
	ds_read_b64_tr_b16 v[124:125], v182 offset:31744
	v_fmac_f32_e32 v187, s4, v99
	v_exp_f32_e32 v77, v77
	v_exp_f32_e32 v85, v73
	v_exp_f32_e32 v130, v221
	v_exp_f32_e32 v101, v187
	s_add_u32 s52, s52, 16
	s_waitcnt lgkmcnt(6)
	v_mfma_f32_32x32x16_bf16 v[36:51], v[114:117], v[68:71], v[36:51]
	ds_read_b64_tr_b16 v[114:115], v72 offset:28736
	ds_read_b64_tr_b16 v[116:117], v72 offset:29760
	ds_read_b64_tr_b16 v[182:183], v72 offset:14400
	ds_read_b64_tr_b16 v[184:185], v72 offset:15424
	ds_read_b64_tr_b16 v[80:81], v72 offset:30784
	ds_read_b64_tr_b16 v[82:83], v72 offset:31808
	s_addc_u32 s53, s53, 0
	v_lshl_add_u64 v[174:175], v[174:175], 0, s[48:49]
	s_cmp_lg_u32 s72, s50
	v_lshl_add_u64 v[176:177], v[176:177], 0, s[48:49]
	s_waitcnt lgkmcnt(8)
	v_mfma_f32_32x32x16_bf16 v[4:19], v[118:121], v[94:97], v[4:19]
	s_waitcnt lgkmcnt(4)
	v_mfma_f32_32x32x16_bf16 v[20:35], v[114:117], v[68:71], v[20:35]
	v_add_f32_e64 v68, v88, v86
	v_add_f32_e64 v69, v89, v87
	v_add_f32_e64 v70, v90, v102
	v_add_f32_e64 v71, v91, v103
	v_add_f32_e64 v86, v74, v104
	v_add_f32_e64 v87, v75, v105
	v_pk_add_f32 v[72:73], v[70:71], v[68:69]
	v_cvt_pk_bf16_f32 v68, v104, v106
	v_cvt_pk_bf16_f32 v69, v108, v110
	v_cvt_pk_bf16_f32 v70, v246, v250
	v_cvt_pk_bf16_f32 v71, v188, v130
	v_pk_add_f32 v[86:87], v[86:87], v[72:73]
	v_pk_add_f32 v[88:89], v[76:77], v[106:107]
	v_cvt_pk_bf16_f32 v72, v75, v77
	v_cvt_pk_bf16_f32 v73, v93, v79
	v_cvt_pk_bf16_f32 v74, v113, v249
	v_cvt_pk_bf16_f32 v75, v85, v101
	v_mfma_f32_32x32x16_bf16 v[52:67], v[126:129], v[68:71], v[52:67]
	v_add_f32_e64 v76, v88, v86
	v_add_f32_e64 v77, v89, v87
	v_add_f32_e64 v86, v92, v108
	v_add_f32_e64 v87, v93, v109
	v_add_f32_e64 v78, v78, v110
	v_add_f32_e64 v79, v79, v111
	v_pk_add_f32 v[76:77], v[86:87], v[76:77]
	s_nop 0
	v_pk_add_f32 v[76:77], v[78:79], v[76:77]
	v_pk_add_f32 v[78:79], v[112:113], v[246:247]
	v_mfma_f32_32x32x16_bf16 v[36:51], v[122:125], v[72:75], v[36:51]
	v_add_f32_e64 v76, v78, v76
	v_add_f32_e64 v77, v79, v77
	s_waitcnt lgkmcnt(2)
	v_mfma_f32_32x32x16_bf16 v[4:19], v[182:185], v[68:71], v[4:19]
	v_add_f32_e64 v68, v248, v250
	v_add_f32_e64 v69, v249, v251
	v_add_f32_e64 v70, v84, v188
	v_add_f32_e64 v71, v85, v189
	v_add_f32_e64 v68, v68, v76
	v_add_f32_e64 v69, v69, v77
	v_pk_add_f32 v[68:69], v[70:71], v[68:69]
	v_pk_add_f32 v[70:71], v[100:101], v[130:131]
	s_waitcnt lgkmcnt(0)
	v_mfma_f32_32x32x16_bf16 v[20:35], v[80:83], v[72:75], v[20:35]
	v_add_f32_e64 v68, v70, v68
	v_add_f32_e64 v69, v71, v69
	v_add_f32_e64 v172, v172, v68
	v_add_f32_e64 v173, v173, v69
	s_cbranch_scc0 .LBB0_735
	s_branch .LBB0_718
